# baseline (speedup 1.0000x reference)
; __device__ __forceinline__ unsigned cvt_pk_bf16(float lo, float hi) { unsigned r; asm volatile("v_cvt_pk_bf16_f32 %0, %1, %2" : "=v"(r) : "v"(lo), "v"(hi)); return r; }
;     __device__ __forceinline__ void operator()(const f32x4 (&acc)[2][2][4][2], const Unit& u, int wr, int wc, int fr, int fq) const {
;         const int colt = u.pn * BM, seg = colt >> 10, cseg = colt & 1023;
;         const float sc = seg == 0 ? qsa : (seg == 4 ? qsb : 1.f);
;         const bool kv = (seg == 1) || (seg == 2) || (seg == 5) || (seg == 6);
;         const int kvi = seg == 1 ? 0 : (seg == 2 ? 1 : (seg == 5 ? 2 : 3));
;         const bool sample = u.pm >= 128;
;         const int row0 = u.pm * BM + wr * 64 + fr, col0 = wc * 32 + 8 * fq;
;         float* op = out + (sample ? (size_t)202637312 + (size_t)kvi * 524288 : (size_t)68157440 + (size_t)kvi * 33554432);
;         bf16_t* ck = CK + (size_t)kvi * 34603008;
;     ...
; #pragma unroll
;         for (int ai = 0; ai < 2; ++ai)
; #pragma unroll
;             for (int m = 0; m < 4; ++m) {
;                 const int row = row0 + ai * HALF + m * 16;
;                 bf16_t* zr = Z + (size_t)row * 8192 + colt + col0;
;                 const int rr = sample ? row - 32768 : row;
; #pragma unroll
;                 for (int bj = 0; bj < 2; ++bj) {
;                     const f32x4 v0 = acc[ai][bj][m][0] * sc, v1 = acc[ai][bj][m][1] * sc;
;                     u32x4 w; w.x = cvt_pk_bf16(v0[0], v0[1]); w.y = cvt_pk_bf16(v0[2], v0[3]); w.z = cvt_pk_bf16(v1[0], v1[1]); w.w = cvt_pk_bf16(v1[2], v1[3]);
;                     *(u32x4*)(zr + bj * HALF) = w;
;                     if (kv) {
;                         const int c = cseg + bj * HALF + col0;
;                         float* o = op + (size_t)rr * 1024 + c;
;                         __builtin_nontemporal_store(v0, (f32x4*)o); __builtin_nontemporal_store(v1, (f32x4*)(o + 4));
;                         if (sample) *(u32x4*)(ck + ((size_t)((rr >> 4) * 1040 + 1024 + (rr & 15))) * 1024 + c) = w;
;                     }
.LBB0_147:
	s_cmp_eq_u32 s19, 4
	s_cselect_b64 vcc, -1, 0
	s_cmp_gt_u32 s2, 3
	v_cndmask_b32_e32 v128, 1.0, v167, vcc
	s_cselect_b64 vcc, -1, 0
	s_add_i32 s2, s19, -1
	s_and_b32 s21, s2, -6
	s_cmp_eq_u32 s21, 0
	s_cselect_b64 s[36:37], -1, 0
	s_and_b64 s[34:35], s[34:35], exec
	s_cselect_b32 s2, 2, 3
	s_cmp_lg_u32 s19, 2
	s_cselect_b32 s2, s2, 1
	s_and_b64 s[30:31], s[30:31], exec
	s_cselect_b32 s2, 0, s2
	s_and_b64 s[30:31], s[6:7], exec
	s_cselect_b32 s29, 25, 19
	s_cselect_b32 s19, s53, 0x30500000
	s_lshl_b64 s[30:31], s[2:3], s29
	s_lshl_b64 s[30:31], s[30:31], 2
	s_add_u32 s29, s62, s30
	s_addc_u32 s30, s63, s31
	s_add_u32 s34, s29, s19
	v_lshl_add_u32 v156, s8, 8, v143
	s_addc_u32 s35, s30, 0
	s_mul_i32 s2, s2, 0x4200000
	v_ashrrev_i32_e32 v157, 31, v156
	v_cndmask_b32_e32 v154, v168, v128, vcc
	s_add_u32 s30, s70, s2
	s_waitcnt lgkmcnt(0)
	v_lshlrev_b64 v[128:129], 14, v[156:157]
	s_addc_u32 s31, s71, 0
	s_ashr_i32 s29, s28, 31
	v_lshl_add_u64 v[128:129], s[68:69], 0, v[128:129]
	v_lshl_add_u64 v[128:129], s[28:29], 1, v[128:129]
	v_lshlrev_b32_e32 v140, 1, v142
	v_add_u32_e32 v130, 0xffff8000, v156
	v_lshl_add_u64 v[162:163], v[128:129], 0, v[140:141]
	v_cndmask_b32_e64 v128, v130, v156, s[6:7]
	v_ashrrev_i32_e32 v129, 31, v128
	v_lshlrev_b64 v[128:129], 12, v[128:129]
	v_lshl_add_u64 v[160:161], s[34:35], 0, v[128:129]
	v_lshrrev_b32_e32 v128, 4, v130
	v_or_b32_e32 v169, s9, v142
	v_mad_u64_u32 v[128:129], s[8:9], v128, s54, v[144:145]
	v_ashrrev_i32_e32 v129, 31, v128
	v_lshlrev_b64 v[128:129], 11, v[128:129]
	s_cmp_lg_u32 s21, 0
	v_lshl_add_u64 v[158:159], s[30:31], 0, v[128:129]
	v_pk_mul_f32 v[126:127], v[154:155], v[126:127] op_sel_hi:[0,1]
	v_pk_mul_f32 v[124:125], v[154:155], v[124:125] op_sel_hi:[0,1]
	v_pk_mul_f32 v[130:131], v[154:155], v[122:123] op_sel_hi:[0,1]
	v_pk_mul_f32 v[128:129], v[154:155], v[120:121] op_sel_hi:[0,1]
	v_cvt_pk_bf16_f32 v120, v124, v125
	v_cvt_pk_bf16_f32 v121, v126, v127
	v_cvt_pk_bf16_f32 v122, v128, v129
	v_cvt_pk_bf16_f32 v123, v130, v131
	global_store_dwordx4 v[162:163], v[120:123], off nt
	s_cbranch_scc1 .LBB0_150
	v_lshlrev_b32_e32 v170, 2, v169
	v_mov_b32_e32 v171, v141
	v_lshl_add_u64 v[170:171], v[160:161], 0, v[170:171]
	s_andn2_b64 vcc, exec, s[26:27]
	global_store_dwordx4 v[170:171], v[124:127], off nt
	global_store_dwordx4 v[170:171], v[128:131], off offset:16 nt
	s_cbranch_vccnz .LBB0_150
	v_lshlrev_b32_e32 v124, 1, v169
	v_mov_b32_e32 v125, v141
	v_lshl_add_u64 v[124:125], v[158:159], 0, v[124:125]
	global_store_dwordx4 v[124:125], v[120:123], off
.LBB0_150:
	v_mov_b32_e32 v155, v154
	v_mov_b32_e32 v124, v154
	v_mov_b32_e32 v125, v154
	v_cndmask_b32_e64 v126, 0, 1, s[36:37]
	v_pk_mul_f32 v[118:119], v[124:125], v[118:119]
	v_pk_mul_f32 v[116:117], v[154:155], v[116:117]
	v_pk_mul_f32 v[122:123], v[124:125], v[114:115]
	v_pk_mul_f32 v[120:121], v[154:155], v[112:113]
	v_cmp_ne_u32_e64 s[8:9], 1, v126
	s_andn2_b64 vcc, exec, s[36:37]
	v_cvt_pk_bf16_f32 v112, v116, v117
	v_cvt_pk_bf16_f32 v113, v118, v119
	v_cvt_pk_bf16_f32 v114, v120, v121
	v_cvt_pk_bf16_f32 v115, v122, v123
	global_store_dwordx4 v[162:163], v[112:115], off offset:256 nt
	s_cbranch_vccnz .LBB0_153
	v_lshlrev_b32_e32 v126, 2, v169
	v_mov_b32_e32 v127, v141
	v_lshl_add_u64 v[126:127], v[160:161], 0, v[126:127]
	s_andn2_b64 vcc, exec, s[26:27]
	global_store_dwordx4 v[126:127], v[116:119], off offset:512 nt
	global_store_dwordx4 v[126:127], v[120:123], off offset:528 nt
	s_cbranch_vccnz .LBB0_153
	v_lshlrev_b32_e32 v116, 1, v169
	v_mov_b32_e32 v117, v141
	v_lshl_add_u64 v[116:117], v[158:159], 0, v[116:117]
	global_store_dwordx4 v[116:117], v[112:115], off offset:256
.LBB0_153:
	s_nop 1
	v_or_b32_e32 v112, 16, v156
	v_ashrrev_i32_e32 v113, 31, v112
	v_lshlrev_b64 v[114:115], 14, v[112:113]
	v_lshl_add_u64 v[114:115], s[68:69], 0, v[114:115]
	v_lshl_add_u64 v[114:115], s[28:29], 1, v[114:115]
	v_lshl_add_u64 v[120:121], v[114:115], 0, v[140:141]
	v_add_u32_e32 v114, 0xffff8010, v156
	v_cndmask_b32_e64 v112, v114, v112, s[6:7]
	v_ashrrev_i32_e32 v113, 31, v112
	v_lshlrev_b64 v[112:113], 12, v[112:113]
	v_lshl_add_u64 v[118:119], s[34:35], 0, v[112:113]
	v_lshrrev_b32_e32 v112, 4, v114
	v_mad_u64_u32 v[112:113], s[36:37], v112, s54, v[144:145]
	v_ashrrev_i32_e32 v113, 31, v112
	v_lshlrev_b64 v[112:113], 11, v[112:113]
	v_lshl_add_u64 v[116:117], s[30:31], 0, v[112:113]
	v_pk_mul_f32 v[110:111], v[124:125], v[110:111]
	v_pk_mul_f32 v[108:109], v[154:155], v[108:109]
	v_pk_mul_f32 v[114:115], v[124:125], v[106:107]
	v_pk_mul_f32 v[112:113], v[154:155], v[104:105]
	s_and_b64 vcc, exec, s[8:9]
	v_cvt_pk_bf16_f32 v104, v108, v109
	v_cvt_pk_bf16_f32 v105, v110, v111
	v_cvt_pk_bf16_f32 v106, v112, v113
	v_cvt_pk_bf16_f32 v107, v114, v115
	global_store_dwordx4 v[120:121], v[104:107], off nt
	s_cbranch_vccnz .LBB0_156
	v_lshlrev_b32_e32 v122, 2, v169
	v_mov_b32_e32 v123, v141
	v_lshl_add_u64 v[122:123], v[118:119], 0, v[122:123]
	s_andn2_b64 vcc, exec, s[26:27]
	global_store_dwordx4 v[122:123], v[108:111], off nt
	global_store_dwordx4 v[122:123], v[112:115], off offset:16 nt
	s_cbranch_vccnz .LBB0_156
	v_lshlrev_b32_e32 v108, 1, v169
	v_mov_b32_e32 v109, v141
	v_lshl_add_u64 v[108:109], v[116:117], 0, v[108:109]
	global_store_dwordx4 v[108:109], v[104:107], off
; __device__ __forceinline__ unsigned cvt_pk_bf16(float lo, float hi) { unsigned r; asm volatile("v_cvt_pk_bf16_f32 %0, %1, %2" : "=v"(r) : "v"(lo), "v"(hi)); return r; }
;     __device__ __forceinline__ void operator()(const f32x4 (&acc)[2][2][4][2], const Unit& u, int wr, int wc, int fr, int fq) const {
;     ...
; #pragma unroll
;         for (int ai = 0; ai < 2; ++ai)
; #pragma unroll
;             for (int m = 0; m < 4; ++m) {
;                 const int row = row0 + ai * HALF + m * 16;
;                 bf16_t* zr = Z + (size_t)row * 8192 + colt + col0;
;                 const int rr = sample ? row - 32768 : row;
; #pragma unroll
;                 for (int bj = 0; bj < 2; ++bj) {
;                     const f32x4 v0 = acc[ai][bj][m][0] * sc, v1 = acc[ai][bj][m][1] * sc;
;                     u32x4 w; w.x = cvt_pk_bf16(v0[0], v0[1]); w.y = cvt_pk_bf16(v0[2], v0[3]); w.z = cvt_pk_bf16(v1[0], v1[1]); w.w = cvt_pk_bf16(v1[2], v1[3]);
;                     *(u32x4*)(zr + bj * HALF) = w;
;                     if (kv) {
;                         const int c = cseg + bj * HALF + col0;
;                         float* o = op + (size_t)rr * 1024 + c;
;                         __builtin_nontemporal_store(v0, (f32x4*)o); __builtin_nontemporal_store(v1, (f32x4*)(o + 4));
;                         if (sample) *(u32x4*)(ck + ((size_t)((rr >> 4) * 1040 + 1024 + (rr & 15))) * 1024 + c) = w;
;                     }
.LBB0_156:
	v_mov_b32_e32 v108, v154
	v_mov_b32_e32 v109, v154
	v_pk_mul_f32 v[102:103], v[108:109], v[102:103]
	v_pk_mul_f32 v[100:101], v[154:155], v[100:101]
	v_pk_mul_f32 v[106:107], v[108:109], v[98:99]
	v_pk_mul_f32 v[104:105], v[154:155], v[96:97]
	s_and_b64 vcc, exec, s[8:9]
	v_cvt_pk_bf16_f32 v96, v100, v101
	v_cvt_pk_bf16_f32 v97, v102, v103
	v_cvt_pk_bf16_f32 v98, v104, v105
	v_cvt_pk_bf16_f32 v99, v106, v107
	global_store_dwordx4 v[120:121], v[96:99], off offset:256 nt
	s_cbranch_vccnz .LBB0_159
	v_lshlrev_b32_e32 v110, 2, v169
	v_mov_b32_e32 v111, v141
	v_lshl_add_u64 v[110:111], v[118:119], 0, v[110:111]
	s_andn2_b64 vcc, exec, s[26:27]
	global_store_dwordx4 v[110:111], v[100:103], off offset:512 nt
	global_store_dwordx4 v[110:111], v[104:107], off offset:528 nt
	s_cbranch_vccnz .LBB0_159
	v_lshlrev_b32_e32 v100, 1, v169
	v_mov_b32_e32 v101, v141
	v_lshl_add_u64 v[100:101], v[116:117], 0, v[100:101]
	global_store_dwordx4 v[100:101], v[96:99], off offset:256
.LBB0_159:
	s_nop 1
	v_or_b32_e32 v96, 32, v156
	v_ashrrev_i32_e32 v97, 31, v96
	v_lshlrev_b64 v[98:99], 14, v[96:97]
	v_lshl_add_u64 v[98:99], s[68:69], 0, v[98:99]
	v_lshl_add_u64 v[98:99], s[28:29], 1, v[98:99]
	v_lshl_add_u64 v[104:105], v[98:99], 0, v[140:141]
	v_add_u32_e32 v98, 0xffff8020, v156
	v_cndmask_b32_e64 v96, v98, v96, s[6:7]
	v_ashrrev_i32_e32 v97, 31, v96
	v_lshlrev_b64 v[96:97], 12, v[96:97]
	v_lshl_add_u64 v[102:103], s[34:35], 0, v[96:97]
	v_lshrrev_b32_e32 v96, 4, v98
	v_mad_u64_u32 v[96:97], s[36:37], v96, s54, v[144:145]
	v_ashrrev_i32_e32 v97, 31, v96
	v_lshlrev_b64 v[96:97], 11, v[96:97]
	v_lshl_add_u64 v[100:101], s[30:31], 0, v[96:97]
	v_pk_mul_f32 v[94:95], v[108:109], v[94:95]
	v_pk_mul_f32 v[92:93], v[154:155], v[92:93]
	v_pk_mul_f32 v[98:99], v[108:109], v[90:91]
	v_pk_mul_f32 v[96:97], v[154:155], v[88:89]
	s_and_b64 vcc, exec, s[8:9]
	v_cvt_pk_bf16_f32 v88, v92, v93
	v_cvt_pk_bf16_f32 v89, v94, v95
	v_cvt_pk_bf16_f32 v90, v96, v97
	v_cvt_pk_bf16_f32 v91, v98, v99
	global_store_dwordx4 v[104:105], v[88:91], off nt
	s_cbranch_vccnz .LBB0_162
	v_lshlrev_b32_e32 v106, 2, v169
	v_mov_b32_e32 v107, v141
	v_lshl_add_u64 v[106:107], v[102:103], 0, v[106:107]
	s_andn2_b64 vcc, exec, s[26:27]
	global_store_dwordx4 v[106:107], v[92:95], off nt
	global_store_dwordx4 v[106:107], v[96:99], off offset:16 nt
	s_cbranch_vccnz .LBB0_162
	v_lshlrev_b32_e32 v92, 1, v169
	v_mov_b32_e32 v93, v141
	v_lshl_add_u64 v[92:93], v[100:101], 0, v[92:93]
	global_store_dwordx4 v[92:93], v[88:91], off
.LBB0_162:
	v_mov_b32_e32 v92, v154
	v_mov_b32_e32 v93, v154
	v_pk_mul_f32 v[86:87], v[92:93], v[86:87]
	v_pk_mul_f32 v[84:85], v[154:155], v[84:85]
	v_pk_mul_f32 v[90:91], v[92:93], v[82:83]
	v_pk_mul_f32 v[88:89], v[154:155], v[80:81]
	s_and_b64 vcc, exec, s[8:9]
	v_cvt_pk_bf16_f32 v80, v84, v85
	v_cvt_pk_bf16_f32 v81, v86, v87
	v_cvt_pk_bf16_f32 v82, v88, v89
	v_cvt_pk_bf16_f32 v83, v90, v91
	global_store_dwordx4 v[104:105], v[80:83], off offset:256 nt
	s_cbranch_vccnz .LBB0_165
	v_lshlrev_b32_e32 v94, 2, v169
	v_mov_b32_e32 v95, v141
	v_lshl_add_u64 v[94:95], v[102:103], 0, v[94:95]
	s_andn2_b64 vcc, exec, s[26:27]
	global_store_dwordx4 v[94:95], v[84:87], off offset:512 nt
	global_store_dwordx4 v[94:95], v[88:91], off offset:528 nt
	s_cbranch_vccnz .LBB0_165
	v_lshlrev_b32_e32 v84, 1, v169
	v_mov_b32_e32 v85, v141
	v_lshl_add_u64 v[84:85], v[100:101], 0, v[84:85]
	global_store_dwordx4 v[84:85], v[80:83], off offset:256
.LBB0_165:
	s_nop 1
	v_or_b32_e32 v80, 48, v156
	v_ashrrev_i32_e32 v81, 31, v80
	v_lshlrev_b64 v[82:83], 14, v[80:81]
	v_lshl_add_u64 v[82:83], s[68:69], 0, v[82:83]
	v_lshl_add_u64 v[82:83], s[28:29], 1, v[82:83]
	v_lshl_add_u64 v[88:89], v[82:83], 0, v[140:141]
	v_add_u32_e32 v82, 0xffff8030, v156
	v_cndmask_b32_e64 v80, v82, v80, s[6:7]
	v_ashrrev_i32_e32 v81, 31, v80
	v_lshlrev_b64 v[80:81], 12, v[80:81]
	v_lshl_add_u64 v[86:87], s[34:35], 0, v[80:81]
	v_lshrrev_b32_e32 v80, 4, v82
	v_mad_u64_u32 v[80:81], s[36:37], v80, s54, v[144:145]
	v_ashrrev_i32_e32 v81, 31, v80
	v_lshlrev_b64 v[80:81], 11, v[80:81]
	v_lshl_add_u64 v[84:85], s[30:31], 0, v[80:81]
	v_pk_mul_f32 v[78:79], v[92:93], v[78:79]
	v_pk_mul_f32 v[76:77], v[154:155], v[76:77]
	v_pk_mul_f32 v[82:83], v[92:93], v[74:75]
	v_pk_mul_f32 v[80:81], v[154:155], v[72:73]
	s_and_b64 vcc, exec, s[8:9]
	v_cvt_pk_bf16_f32 v72, v76, v77
	v_cvt_pk_bf16_f32 v73, v78, v79
	v_cvt_pk_bf16_f32 v74, v80, v81
	v_cvt_pk_bf16_f32 v75, v82, v83
	global_store_dwordx4 v[88:89], v[72:75], off nt
	s_cbranch_vccnz .LBB0_168
	v_lshlrev_b32_e32 v90, 2, v169
	v_mov_b32_e32 v91, v141
	v_lshl_add_u64 v[90:91], v[86:87], 0, v[90:91]
	s_andn2_b64 vcc, exec, s[26:27]
	global_store_dwordx4 v[90:91], v[76:79], off nt
	global_store_dwordx4 v[90:91], v[80:83], off offset:16 nt
	s_cbranch_vccnz .LBB0_168
	v_lshlrev_b32_e32 v76, 1, v169
	v_mov_b32_e32 v77, v141
	v_lshl_add_u64 v[76:77], v[84:85], 0, v[76:77]
	global_store_dwordx4 v[76:77], v[72:75], off
.LBB0_168:
	v_mov_b32_e32 v76, v154
	v_mov_b32_e32 v77, v154
	v_pk_mul_f32 v[70:71], v[76:77], v[70:71]
	v_pk_mul_f32 v[68:69], v[154:155], v[68:69]
	v_pk_mul_f32 v[74:75], v[76:77], v[66:67]
	v_pk_mul_f32 v[72:73], v[154:155], v[64:65]
	s_and_b64 vcc, exec, s[8:9]
	v_cvt_pk_bf16_f32 v64, v68, v69
	v_cvt_pk_bf16_f32 v65, v70, v71
	v_cvt_pk_bf16_f32 v66, v72, v73
	v_cvt_pk_bf16_f32 v67, v74, v75
	global_store_dwordx4 v[88:89], v[64:67], off offset:256 nt
	s_cbranch_vccnz .LBB0_171
	v_lshlrev_b32_e32 v78, 2, v169
	v_mov_b32_e32 v79, v141
	v_lshl_add_u64 v[78:79], v[86:87], 0, v[78:79]
	s_andn2_b64 vcc, exec, s[26:27]
	global_store_dwordx4 v[78:79], v[68:71], off offset:512 nt
	global_store_dwordx4 v[78:79], v[72:75], off offset:528 nt
	s_cbranch_vccnz .LBB0_171
	v_lshlrev_b32_e32 v68, 1, v169
	v_mov_b32_e32 v69, v141
	v_lshl_add_u64 v[68:69], v[84:85], 0, v[68:69]
	global_store_dwordx4 v[68:69], v[64:67], off offset:256
; __device__ __forceinline__ unsigned cvt_pk_bf16(float lo, float hi) { unsigned r; asm volatile("v_cvt_pk_bf16_f32 %0, %1, %2" : "=v"(r) : "v"(lo), "v"(hi)); return r; }
;     __device__ __forceinline__ void operator()(const f32x4 (&acc)[2][2][4][2], const Unit& u, int wr, int wc, int fr, int fq) const {
;     ...
; #pragma unroll
;         for (int ai = 0; ai < 2; ++ai)
; #pragma unroll
;             for (int m = 0; m < 4; ++m) {
;                 const int row = row0 + ai * HALF + m * 16;
;                 bf16_t* zr = Z + (size_t)row * 8192 + colt + col0;
;                 const int rr = sample ? row - 32768 : row;
; #pragma unroll
;                 for (int bj = 0; bj < 2; ++bj) {
;                     const f32x4 v0 = acc[ai][bj][m][0] * sc, v1 = acc[ai][bj][m][1] * sc;
;                     u32x4 w; w.x = cvt_pk_bf16(v0[0], v0[1]); w.y = cvt_pk_bf16(v0[2], v0[3]); w.z = cvt_pk_bf16(v1[0], v1[1]); w.w = cvt_pk_bf16(v1[2], v1[3]);
;                     *(u32x4*)(zr + bj * HALF) = w;
;                     if (kv) {
;                         const int c = cseg + bj * HALF + col0;
;                         float* o = op + (size_t)rr * 1024 + c;
;                         __builtin_nontemporal_store(v0, (f32x4*)o); __builtin_nontemporal_store(v1, (f32x4*)(o + 4));
;                         if (sample) *(u32x4*)(ck + ((size_t)((rr >> 4) * 1040 + 1024 + (rr & 15))) * 1024 + c) = w;
;                     }
.LBB0_171:
	s_nop 1
	v_add_u32_e32 v64, 0x80, v156
	v_ashrrev_i32_e32 v65, 31, v64
	v_lshlrev_b64 v[66:67], 14, v[64:65]
	v_lshl_add_u64 v[66:67], s[68:69], 0, v[66:67]
	v_lshl_add_u64 v[66:67], s[28:29], 1, v[66:67]
	v_lshl_add_u64 v[72:73], v[66:67], 0, v[140:141]
	v_add_u32_e32 v66, 0xffff8080, v156
	v_cndmask_b32_e64 v64, v66, v64, s[6:7]
	v_ashrrev_i32_e32 v65, 31, v64
	v_lshlrev_b64 v[64:65], 12, v[64:65]
	v_lshl_add_u64 v[70:71], s[34:35], 0, v[64:65]
	v_lshrrev_b32_e32 v64, 4, v66
	v_mad_u64_u32 v[64:65], s[36:37], v64, s54, v[144:145]
	v_ashrrev_i32_e32 v65, 31, v64
	v_lshlrev_b64 v[64:65], 11, v[64:65]
	v_lshl_add_u64 v[68:69], s[30:31], 0, v[64:65]
	v_pk_mul_f32 v[62:63], v[76:77], v[62:63]
	v_pk_mul_f32 v[60:61], v[154:155], v[60:61]
	v_pk_mul_f32 v[66:67], v[76:77], v[58:59]
	v_pk_mul_f32 v[64:65], v[154:155], v[56:57]
	s_and_b64 vcc, exec, s[8:9]
	v_cvt_pk_bf16_f32 v56, v60, v61
	v_cvt_pk_bf16_f32 v57, v62, v63
	v_cvt_pk_bf16_f32 v58, v64, v65
	v_cvt_pk_bf16_f32 v59, v66, v67
	global_store_dwordx4 v[72:73], v[56:59], off nt
	s_cbranch_vccnz .LBB0_174
	v_lshlrev_b32_e32 v74, 2, v169
	v_mov_b32_e32 v75, v141
	v_lshl_add_u64 v[74:75], v[70:71], 0, v[74:75]
	s_andn2_b64 vcc, exec, s[26:27]
	global_store_dwordx4 v[74:75], v[60:63], off nt
	global_store_dwordx4 v[74:75], v[64:67], off offset:16 nt
	s_cbranch_vccnz .LBB0_174
	v_lshlrev_b32_e32 v60, 1, v169
	v_mov_b32_e32 v61, v141
	v_lshl_add_u64 v[60:61], v[68:69], 0, v[60:61]
	global_store_dwordx4 v[60:61], v[56:59], off
.LBB0_174:
	v_mov_b32_e32 v60, v154
	v_mov_b32_e32 v61, v154
	v_pk_mul_f32 v[54:55], v[60:61], v[54:55]
	v_pk_mul_f32 v[52:53], v[154:155], v[52:53]
	v_pk_mul_f32 v[58:59], v[60:61], v[50:51]
	v_pk_mul_f32 v[56:57], v[154:155], v[48:49]
	s_and_b64 vcc, exec, s[8:9]
	v_cvt_pk_bf16_f32 v48, v52, v53
	v_cvt_pk_bf16_f32 v49, v54, v55
	v_cvt_pk_bf16_f32 v50, v56, v57
	v_cvt_pk_bf16_f32 v51, v58, v59
	global_store_dwordx4 v[72:73], v[48:51], off offset:256 nt
	s_cbranch_vccnz .LBB0_177
	v_lshlrev_b32_e32 v62, 2, v169
	v_mov_b32_e32 v63, v141
	v_lshl_add_u64 v[62:63], v[70:71], 0, v[62:63]
	s_andn2_b64 vcc, exec, s[26:27]
	global_store_dwordx4 v[62:63], v[52:55], off offset:512 nt
	global_store_dwordx4 v[62:63], v[56:59], off offset:528 nt
	s_cbranch_vccnz .LBB0_177
	v_lshlrev_b32_e32 v52, 1, v169
	v_mov_b32_e32 v53, v141
	v_lshl_add_u64 v[52:53], v[68:69], 0, v[52:53]
	global_store_dwordx4 v[52:53], v[48:51], off offset:256
.LBB0_177:
	s_nop 1
	v_add_u32_e32 v48, 0x90, v156
	v_ashrrev_i32_e32 v49, 31, v48
	v_lshlrev_b64 v[50:51], 14, v[48:49]
	v_lshl_add_u64 v[50:51], s[68:69], 0, v[50:51]
	v_lshl_add_u64 v[50:51], s[28:29], 1, v[50:51]
	v_lshl_add_u64 v[56:57], v[50:51], 0, v[140:141]
	v_add_u32_e32 v50, 0xffff8090, v156
	v_cndmask_b32_e64 v48, v50, v48, s[6:7]
	v_ashrrev_i32_e32 v49, 31, v48
	v_lshlrev_b64 v[48:49], 12, v[48:49]
	v_lshl_add_u64 v[54:55], s[34:35], 0, v[48:49]
	v_lshrrev_b32_e32 v48, 4, v50
	v_mad_u64_u32 v[48:49], s[36:37], v48, s54, v[144:145]
	v_ashrrev_i32_e32 v49, 31, v48
	v_lshlrev_b64 v[48:49], 11, v[48:49]
	v_lshl_add_u64 v[52:53], s[30:31], 0, v[48:49]
	v_pk_mul_f32 v[46:47], v[60:61], v[46:47]
	v_pk_mul_f32 v[44:45], v[154:155], v[44:45]
	v_pk_mul_f32 v[50:51], v[60:61], v[42:43]
	v_pk_mul_f32 v[48:49], v[154:155], v[40:41]
	s_and_b64 vcc, exec, s[8:9]
	v_cvt_pk_bf16_f32 v40, v44, v45
	v_cvt_pk_bf16_f32 v41, v46, v47
	v_cvt_pk_bf16_f32 v42, v48, v49
	v_cvt_pk_bf16_f32 v43, v50, v51
	global_store_dwordx4 v[56:57], v[40:43], off nt
	s_cbranch_vccnz .LBB0_180
	v_lshlrev_b32_e32 v58, 2, v169
	v_mov_b32_e32 v59, v141
	v_lshl_add_u64 v[58:59], v[54:55], 0, v[58:59]
	s_andn2_b64 vcc, exec, s[26:27]
	global_store_dwordx4 v[58:59], v[44:47], off nt
	global_store_dwordx4 v[58:59], v[48:51], off offset:16 nt
	s_cbranch_vccnz .LBB0_180
	v_lshlrev_b32_e32 v44, 1, v169
	v_mov_b32_e32 v45, v141
	v_lshl_add_u64 v[44:45], v[52:53], 0, v[44:45]
	global_store_dwordx4 v[44:45], v[40:43], off
.LBB0_180:
	v_mov_b32_e32 v44, v154
	v_mov_b32_e32 v45, v154
	v_pk_mul_f32 v[38:39], v[44:45], v[38:39]
	v_pk_mul_f32 v[36:37], v[154:155], v[36:37]
	v_pk_mul_f32 v[42:43], v[44:45], v[34:35]
	v_pk_mul_f32 v[40:41], v[154:155], v[32:33]
	s_and_b64 vcc, exec, s[8:9]
	v_cvt_pk_bf16_f32 v32, v36, v37
	v_cvt_pk_bf16_f32 v33, v38, v39
	v_cvt_pk_bf16_f32 v34, v40, v41
	v_cvt_pk_bf16_f32 v35, v42, v43
	global_store_dwordx4 v[56:57], v[32:35], off offset:256 nt
	s_cbranch_vccnz .LBB0_183
	v_lshlrev_b32_e32 v46, 2, v169
	v_mov_b32_e32 v47, v141
	v_lshl_add_u64 v[46:47], v[54:55], 0, v[46:47]
	s_andn2_b64 vcc, exec, s[26:27]
	global_store_dwordx4 v[46:47], v[36:39], off offset:512 nt
	global_store_dwordx4 v[46:47], v[40:43], off offset:528 nt
	s_cbranch_vccnz .LBB0_183
	v_lshlrev_b32_e32 v36, 1, v169
	v_mov_b32_e32 v37, v141
	v_lshl_add_u64 v[36:37], v[52:53], 0, v[36:37]
	global_store_dwordx4 v[36:37], v[32:35], off offset:256
; __device__ __forceinline__ unsigned cvt_pk_bf16(float lo, float hi) { unsigned r; asm volatile("v_cvt_pk_bf16_f32 %0, %1, %2" : "=v"(r) : "v"(lo), "v"(hi)); return r; }
;     __device__ __forceinline__ void operator()(const f32x4 (&acc)[2][2][4][2], const Unit& u, int wr, int wc, int fr, int fq) const {
;     ...
; #pragma unroll
;         for (int ai = 0; ai < 2; ++ai)
; #pragma unroll
;             for (int m = 0; m < 4; ++m) {
;                 const int row = row0 + ai * HALF + m * 16;
;                 bf16_t* zr = Z + (size_t)row * 8192 + colt + col0;
;                 const int rr = sample ? row - 32768 : row;
; #pragma unroll
;                 for (int bj = 0; bj < 2; ++bj) {
;                     const f32x4 v0 = acc[ai][bj][m][0] * sc, v1 = acc[ai][bj][m][1] * sc;
;                     u32x4 w; w.x = cvt_pk_bf16(v0[0], v0[1]); w.y = cvt_pk_bf16(v0[2], v0[3]); w.z = cvt_pk_bf16(v1[0], v1[1]); w.w = cvt_pk_bf16(v1[2], v1[3]);
;                     *(u32x4*)(zr + bj * HALF) = w;
;                     if (kv) {
;                         const int c = cseg + bj * HALF + col0;
;                         float* o = op + (size_t)rr * 1024 + c;
;                         __builtin_nontemporal_store(v0, (f32x4*)o); __builtin_nontemporal_store(v1, (f32x4*)(o + 4));
;                         if (sample) *(u32x4*)(ck + ((size_t)((rr >> 4) * 1040 + 1024 + (rr & 15))) * 1024 + c) = w;
;                     }
.LBB0_183:
	s_nop 1
	v_add_u32_e32 v32, 0xa0, v156
	v_ashrrev_i32_e32 v33, 31, v32
	v_lshlrev_b64 v[34:35], 14, v[32:33]
	v_lshl_add_u64 v[34:35], s[68:69], 0, v[34:35]
	v_lshl_add_u64 v[34:35], s[28:29], 1, v[34:35]
	v_lshl_add_u64 v[40:41], v[34:35], 0, v[140:141]
	v_add_u32_e32 v34, 0xffff80a0, v156
	v_cndmask_b32_e64 v32, v34, v32, s[6:7]
	v_ashrrev_i32_e32 v33, 31, v32
	v_lshlrev_b64 v[32:33], 12, v[32:33]
	v_lshl_add_u64 v[38:39], s[34:35], 0, v[32:33]
	v_lshrrev_b32_e32 v32, 4, v34
	v_mad_u64_u32 v[32:33], s[36:37], v32, s54, v[144:145]
	v_ashrrev_i32_e32 v33, 31, v32
	v_lshlrev_b64 v[32:33], 11, v[32:33]
	v_lshl_add_u64 v[36:37], s[30:31], 0, v[32:33]
	v_pk_mul_f32 v[30:31], v[44:45], v[30:31]
	v_pk_mul_f32 v[28:29], v[154:155], v[28:29]
	v_pk_mul_f32 v[34:35], v[44:45], v[26:27]
	v_pk_mul_f32 v[32:33], v[154:155], v[24:25]
	s_and_b64 vcc, exec, s[8:9]
	v_cvt_pk_bf16_f32 v24, v28, v29
	v_cvt_pk_bf16_f32 v25, v30, v31
	v_cvt_pk_bf16_f32 v26, v32, v33
	v_cvt_pk_bf16_f32 v27, v34, v35
	global_store_dwordx4 v[40:41], v[24:27], off nt
	s_cbranch_vccnz .LBB0_186
	v_lshlrev_b32_e32 v42, 2, v169
	v_mov_b32_e32 v43, v141
	v_lshl_add_u64 v[42:43], v[38:39], 0, v[42:43]
	s_andn2_b64 vcc, exec, s[26:27]
	global_store_dwordx4 v[42:43], v[28:31], off nt
	global_store_dwordx4 v[42:43], v[32:35], off offset:16 nt
	s_cbranch_vccnz .LBB0_186
	v_lshlrev_b32_e32 v28, 1, v169
	v_mov_b32_e32 v29, v141
	v_lshl_add_u64 v[28:29], v[36:37], 0, v[28:29]
	global_store_dwordx4 v[28:29], v[24:27], off
.LBB0_186:
	v_mov_b32_e32 v28, v154
	v_mov_b32_e32 v29, v154
	v_pk_mul_f32 v[22:23], v[28:29], v[22:23]
	v_pk_mul_f32 v[20:21], v[154:155], v[20:21]
	v_pk_mul_f32 v[26:27], v[28:29], v[18:19]
	v_pk_mul_f32 v[24:25], v[154:155], v[16:17]
	s_and_b64 vcc, exec, s[8:9]
	v_cvt_pk_bf16_f32 v16, v20, v21
	v_cvt_pk_bf16_f32 v17, v22, v23
	v_cvt_pk_bf16_f32 v18, v24, v25
	v_cvt_pk_bf16_f32 v19, v26, v27
	global_store_dwordx4 v[40:41], v[16:19], off offset:256 nt
	s_cbranch_vccnz .LBB0_189
	v_lshlrev_b32_e32 v30, 2, v169
	v_mov_b32_e32 v31, v141
	v_lshl_add_u64 v[30:31], v[38:39], 0, v[30:31]
	s_andn2_b64 vcc, exec, s[26:27]
	global_store_dwordx4 v[30:31], v[20:23], off offset:512 nt
	global_store_dwordx4 v[30:31], v[24:27], off offset:528 nt
	s_cbranch_vccnz .LBB0_189
	v_lshlrev_b32_e32 v20, 1, v169
	v_mov_b32_e32 v21, v141
	v_lshl_add_u64 v[20:21], v[36:37], 0, v[20:21]
	global_store_dwordx4 v[20:21], v[16:19], off offset:256
.LBB0_189:
	s_nop 1
	v_add_u32_e32 v16, 0xb0, v156
	v_ashrrev_i32_e32 v17, 31, v16
	v_lshlrev_b64 v[18:19], 14, v[16:17]
	v_lshl_add_u64 v[18:19], s[68:69], 0, v[18:19]
	v_lshl_add_u64 v[18:19], s[28:29], 1, v[18:19]
	v_lshl_add_u64 v[24:25], v[18:19], 0, v[140:141]
	v_add_u32_e32 v18, 0xffff80b0, v156
	v_cndmask_b32_e64 v16, v18, v16, s[6:7]
	v_ashrrev_i32_e32 v17, 31, v16
	v_lshlrev_b64 v[16:17], 12, v[16:17]
	v_lshl_add_u64 v[22:23], s[34:35], 0, v[16:17]
	v_lshrrev_b32_e32 v16, 4, v18
	v_mad_u64_u32 v[16:17], s[6:7], v16, s54, v[144:145]
	v_ashrrev_i32_e32 v17, 31, v16
	v_lshlrev_b64 v[16:17], 11, v[16:17]
	v_lshl_add_u64 v[20:21], s[30:31], 0, v[16:17]
	v_pk_mul_f32 v[14:15], v[28:29], v[14:15]
	v_pk_mul_f32 v[12:13], v[154:155], v[12:13]
	v_pk_mul_f32 v[18:19], v[28:29], v[10:11]
	v_pk_mul_f32 v[16:17], v[154:155], v[8:9]
	s_and_b64 vcc, exec, s[8:9]
	v_cvt_pk_bf16_f32 v8, v12, v13
	v_cvt_pk_bf16_f32 v9, v14, v15
	v_cvt_pk_bf16_f32 v10, v16, v17
	v_cvt_pk_bf16_f32 v11, v18, v19
	global_store_dwordx4 v[24:25], v[8:11], off nt
	s_cbranch_vccnz .LBB0_192
	v_lshlrev_b32_e32 v140, 2, v169
	v_lshl_add_u64 v[26:27], v[22:23], 0, v[140:141]
	s_andn2_b64 vcc, exec, s[26:27]
	global_store_dwordx4 v[26:27], v[12:15], off nt
	global_store_dwordx4 v[26:27], v[16:19], off offset:16 nt
	s_cbranch_vccnz .LBB0_192
	v_lshlrev_b32_e32 v140, 1, v169
	v_lshl_add_u64 v[12:13], v[20:21], 0, v[140:141]
	global_store_dwordx4 v[12:13], v[8:11], off
.LBB0_192:
	s_nop 1
	v_mov_b32_e32 v8, v154
	v_mov_b32_e32 v9, v154
	v_pk_mul_f32 v[6:7], v[8:9], v[6:7]
	v_pk_mul_f32 v[4:5], v[154:155], v[4:5]
	v_pk_mul_f32 v[10:11], v[8:9], v[2:3]
	v_pk_mul_f32 v[8:9], v[154:155], v[0:1]
	s_and_b64 vcc, exec, s[8:9]
	v_cvt_pk_bf16_f32 v0, v4, v5
	v_cvt_pk_bf16_f32 v1, v6, v7
	v_cvt_pk_bf16_f32 v2, v8, v9
	v_cvt_pk_bf16_f32 v3, v10, v11
	global_store_dwordx4 v[24:25], v[0:3], off offset:256 nt
	s_cbranch_vccnz .LBB0_195
	v_lshlrev_b32_e32 v140, 2, v169
	v_lshl_add_u64 v[12:13], v[22:23], 0, v[140:141]
	s_andn2_b64 vcc, exec, s[26:27]
	global_store_dwordx4 v[12:13], v[4:7], off offset:512 nt
	global_store_dwordx4 v[12:13], v[8:11], off offset:528 nt
	s_cbranch_vccnz .LBB0_195
	v_lshlrev_b32_e32 v140, 1, v169
	v_lshl_add_u64 v[4:5], v[20:21], 0, v[140:141]
	global_store_dwordx4 v[4:5], v[0:3], off offset:256
